# v60 plus P1/P6 unit-loop scheduler computed incrementally (pn += 4 with wrap, pm += 8) instead of the 64-bit index remap per tile
# baseline (speedup 1.0000x reference)
; #define PG8_STAGE(bufoff, gbase, voff) do { _Pragma("unroll") for (int _i = 0; _i < 2; ++_i) \
;         __builtin_amdgcn_global_load_lds((const unsigned*)((const char*)(gbase) + (voff)[_i]), (PG8_LAS unsigned*)(lds + (bufoff) + ldsw + _i * 8192), 16, 0, 0); } while (0)
; #define PG8_WAIT_V(n) asm volatile("s_waitcnt vmcnt(" #n ")" ::: "memory")
; #define PG8_BAR __builtin_amdgcn_s_barrier()
; template <class Epi, class Sched, bool ALIGN_EPI = false, bool SP2 = false, bool ATILED = false>
; __device__ __forceinline__ void gemm_phase(PG8_LAS unsigned char* lds, const Gemm g, const Sched& S, const Epi& E) {
;     ...
;     const int aoff = lds_byte(wr * 64 + fr, fq * 8), boff = lds_byte(wc * 32 + fr, fq * 8);
;     ...
;     Unit cur, nxt; int ui = 0;
;     if (!S.next(0, cur)) return;
;     f32x4 acc[2][2][4][2];
; #pragma unroll
;     for (int a = 0; a < 2; ++a)
; #pragma unroll
;         for (int b = 0; b < 2; ++b)
; #pragma unroll
;             for (int m = 0; m < 4; ++m)
; #pragma unroll
;                 for (int n = 0; n < 2; ++n) acc[a][b][m][n] = (f32x4){0.f, 0.f, 0.f, 0.f};
;     bf16x8 At[4][2], B0[2][2], B1[2][2];
;     const char* cA = (const char*)g.A + (size_t)cur.pm * tstepA; const char* cB = (const char*)g.Bt + (size_t)cur.pn * tstep;
;     S.a_ready(cur);
;     if constexpr (SP2) {
;         PG8_STAGE(PG8_SB(0, 0), cB, voffB); PG8_STAGE(PG8_SB(0, 1), cB + hstep, voffB); PG8_STAGE(PG8_SA(0, 0), cA, voffA); PG8_STAGE(PG8_SA(0, 1), cA + hstepA, voffA);
;         if (wr == 1) PG8_BAR;
;         PG8_WAIT_V(2); PG8_BAR;
;         PG8_STAGE(PG8_SB(1, 0), cB + kstep, voffB); PG8_STAGE(PG8_SA(1, 0), cA + kstepA, voffA); PG8_STAGE(PG8_SB(1, 1), cB + hstep + kstep, voffB);
;         PG8_WAIT_V(6); PG8_BAR;
.LBB0_127:
	s_lshl_b32 s74, s9, 6
	s_lshl_b32 s40, s9, 13
	s_lshl_b32 s41, s8, 5
	s_mov_b64 s[8:9], 0x80
	s_and_b32 s75, s41, 0x60
	s_add_i32 m0, s49, 0x18000
	v_lshl_add_u64 v[6:7], v[6:7], 0, s[8:9]
	s_ashr_i32 s73, s28, 31
	s_lshl_b32 s42, s75, 7
	s_waitcnt vmcnt(2)
	s_barrier
	global_load_lds_dwordx4 v[6:7], off
	v_lshl_add_u64 v[4:5], v[4:5], 0, s[8:9]
	s_add_i32 m0, s49, 0x1a000
	s_add_i32 s76, s49, 0x8000
	s_add_i32 s77, s49, 0xa000
	global_load_lds_dwordx4 v[4:5], off
	v_lshl_add_u64 v[0:1], v[0:1], 0, s[8:9]
	s_mov_b32 m0, s76
	s_add_u32 s38, s62, 0x40080
	global_load_lds_dwordx4 v[0:1], off
	v_lshl_add_u64 v[0:1], v[2:3], 0, s[8:9]
	s_mov_b32 m0, s77
	s_addc_u32 s39, s63, 0
	global_load_lds_dwordx4 v[0:1], off
	s_add_i32 m0, s49, 0x1c000
	v_lshl_add_u64 v[0:1], s[38:39], 0, v[130:131]
	global_load_lds_dwordx4 v[0:1], off
	v_lshl_add_u64 v[0:1], s[38:39], 0, v[134:135]
	s_add_i32 m0, s49, 0x1e000
	s_sext_i32_i16 s81, s0
	global_load_lds_dwordx4 v[0:1], off
	v_bfe_u32 v0, v198, 4, 2
	v_lshlrev_b32_e32 v1, 3, v0
	v_lshlrev_b32_e32 v136, 4, v0
	v_lshlrev_b32_e32 v0, 6, v198
	s_movk_i32 s0, 0x3c0
	v_lshlrev_b32_e32 v2, 2, v198
	v_and_b32_e32 v154, 15, v198
	v_and_or_b32 v0, v0, s0, v136
	v_and_b32_e32 v2, 32, v2
	v_lshl_or_b32 v3, v154, 6, v136
	v_bitop3_b32 v155, s42, v0, v2 bitop3:0xf6
	v_and_or_b32 v0, s41, 32, v1
	v_lshlrev_b32_e32 v1, 8, v198
	v_bitop3_b32 v3, v3, s40, v2 bitop3:0xde
	v_and_b32_e32 v1, 0x38000, v1
	v_lshlrev_b32_e32 v2, 11, v10
	v_or3_b32 v1, v8, v1, v2
	v_add_u32_e32 v140, v1, v9
	v_lshlrev_b32_e32 v1, 4, v11
	v_and_b32_e32 v1, 0x78000, v1
	s_waitcnt vmcnt(6)
	s_cmpk_lt_u32 s1, 0x100
	v_or3_b32 v1, v8, v1, v2
	s_cselect_b64 s[38:39], -1, 0
	v_add_u32_e32 v142, v1, v9
	s_add_i32 s78, 0, 0x10000
	s_add_i32 s79, 0, 0x14000
	v_mbcnt_lo_u32_b32 v1, -1, 0
	v_lshl_add_u64 v[138:139], s[10:11], 0, v[136:137]
	v_mov_b32_e32 v141, v137
	v_mov_b32_e32 v143, v137
	v_mov_b64_e32 v[144:145], 0x1600
	v_mov_b64_e32 v[146:147], 0x15ff
	v_add_u32_e32 v156, s78, v155
	v_add_u32_e32 v157, s79, v155
	v_add_u32_e32 v158, 0, v3
	v_mbcnt_hi_u32_b32 v159, -1, v1
	v_mov_b32_e32 v160, 0x358637bd
	v_lshlrev_b32_e32 v148, 1, v0
	s_movk_i32 s80, 0x1000
	s_barrier
	s_mov_b32 s40, s81
	s_mov_b32 s42, s48
	s_branch .LBB0_130

;     __host__ __device__ bool next(int i, Unit& u) const {
;         const long L = (long)i * G + c; if (L >= nwg) return false;
;         int wgid = (int)L; { const int q = nwg / NXCD, r = nwg % NXCD, xcd = wgid % NXCD, off = wgid / NXCD; wgid = (xcd < r ? xcd * (q + 1) : r * (q + 1) + (xcd - r) * q) + off; }
;         const int nig = WGM * nN, gid = wgid / nig, fm = gid * WGM, gsz = (nM - fm) < WGM ? (nM - fm) : WGM;
;         u.pm = fm + ((wgid % nig) % gsz); u.pn = (wgid % nig) / gsz; return true;
; template <class Epi, class Sched, bool ALIGN_EPI = false, bool SP2 = false, bool ATILED = false>
; __device__ __forceinline__ void gemm_phase(PG8_LAS unsigned char* lds, const Gemm g, const Sched& S, const Epi& E) {
;     ...
;         const bool has_next = S.next(ui + 1, nxt);
;         const char* nA = has_next ? (const char*)g.A + (size_t)nxt.pm * tstepA : cA; const char* nB = has_next ? (const char*)g.Bt + (size_t)nxt.pn * tstep : cB;
.LBB0_130:
	s_add_i32 s72, s72, 1
	s_add_i32 s40, s40, 4
	s_cmp_ge_u32 s40, 22
	s_cselect_b32 s41, 22, 0
	s_cselect_b32 s43, 8, 0
	s_sub_i32 s40, s40, s41
	s_add_i32 s42, s42, s43
	s_cmp_lt_u32 s72, 22
	s_cselect_b64 s[0:1], -1, 0

; #define PG8_STAGE(bufoff, gbase, voff) do { _Pragma("unroll") for (int _i = 0; _i < 2; ++_i) \
;         __builtin_amdgcn_global_load_lds((const unsigned*)((const char*)(gbase) + (voff)[_i]), (PG8_LAS unsigned*)(lds + (bufoff) + ldsw + _i * 8192), 16, 0, 0); } while (0)
; #define PG8_WAIT_V(n) asm volatile("s_waitcnt vmcnt(" #n ")" ::: "memory")
; #define PG8_BAR __builtin_amdgcn_s_barrier()
; template <class Epi, class Sched, bool ALIGN_EPI = false, bool SP2 = false, bool ATILED = false>
; __device__ __forceinline__ void gemm_phase(PG8_LAS unsigned char* lds, const Gemm g, const Sched& S, const Epi& E) {
;     ...
;     const int aoff = lds_byte(wr * 64 + fr, fq * 8), boff = lds_byte(wc * 32 + fr, fq * 8);
;     ...
;     Unit cur, nxt; int ui = 0;
;     if (!S.next(0, cur)) return;
;     f32x4 acc[2][2][4][2];
; #pragma unroll
;     for (int a = 0; a < 2; ++a)
; #pragma unroll
;         for (int b = 0; b < 2; ++b)
; #pragma unroll
;             for (int m = 0; m < 4; ++m)
; #pragma unroll
;                 for (int n = 0; n < 2; ++n) acc[a][b][m][n] = (f32x4){0.f, 0.f, 0.f, 0.f};
;     bf16x8 At[4][2], B0[2][2], B1[2][2];
;     const char* cA = (const char*)g.A + (size_t)cur.pm * tstepA; const char* cB = (const char*)g.Bt + (size_t)cur.pn * tstep;
;     S.a_ready(cur);
;     if constexpr (SP2) {
;         PG8_STAGE(PG8_SB(0, 0), cB, voffB); PG8_STAGE(PG8_SB(0, 1), cB + hstep, voffB); PG8_STAGE(PG8_SA(0, 0), cA, voffA); PG8_STAGE(PG8_SA(0, 1), cA + hstepA, voffA);
;         if (wr == 1) PG8_BAR;
;         PG8_WAIT_V(2); PG8_BAR;
;         PG8_STAGE(PG8_SB(1, 0), cB + kstep, voffB); PG8_STAGE(PG8_SA(1, 0), cA + kstepA, voffA); PG8_STAGE(PG8_SB(1, 1), cB + hstep + kstep, voffB);
;         PG8_WAIT_V(6); PG8_BAR;
.LBB0_811:
	s_lshl_b32 s56, s7, 6
	s_lshl_b32 s12, s7, 13
	s_lshl_b32 s13, s6, 5
	s_mov_b64 s[6:7], 0x80
	s_and_b32 s57, s13, 0x60
	s_add_i32 m0, s19, 0x18000
	v_lshl_add_u64 v[6:7], v[6:7], 0, s[6:7]
	s_ashr_i32 s55, s28, 31
	s_lshl_b32 s14, s57, 7
	s_waitcnt vmcnt(2)
	s_barrier
	global_load_lds_dwordx4 v[6:7], off
	v_lshl_add_u64 v[4:5], v[4:5], 0, s[6:7]
	s_add_i32 m0, s19, 0x1a000
	s_add_i32 s58, s19, 0x8000
	s_add_i32 s59, s19, 0xa000
	global_load_lds_dwordx4 v[4:5], off
	v_lshl_add_u64 v[0:1], v[0:1], 0, s[6:7]
	s_mov_b32 m0, s58
	s_add_u32 s8, s42, 0x40080
	global_load_lds_dwordx4 v[0:1], off
	v_lshl_add_u64 v[0:1], v[2:3], 0, s[6:7]
	s_mov_b32 m0, s59
	s_addc_u32 s9, s43, 0
	global_load_lds_dwordx4 v[0:1], off
	s_add_i32 m0, s19, 0x1c000
	v_lshl_add_u64 v[0:1], s[8:9], 0, v[130:131]
	global_load_lds_dwordx4 v[0:1], off
	v_lshl_add_u64 v[0:1], s[8:9], 0, v[134:135]
	s_add_i32 m0, s19, 0x1e000
	s_sext_i32_i16 s63, s0
	global_load_lds_dwordx4 v[0:1], off
	v_bfe_u32 v0, v198, 4, 2
	v_lshlrev_b32_e32 v1, 3, v0
	v_lshlrev_b32_e32 v136, 4, v0
	v_lshlrev_b32_e32 v0, 6, v198
	s_movk_i32 s0, 0x3c0
	v_lshlrev_b32_e32 v2, 2, v198
	v_and_b32_e32 v154, 15, v198
	v_and_or_b32 v0, v0, s0, v136
	v_and_b32_e32 v2, 32, v2
	v_lshl_or_b32 v3, v154, 6, v136
	v_bitop3_b32 v155, s14, v0, v2 bitop3:0xf6
	v_and_or_b32 v0, s13, 32, v1
	v_lshlrev_b32_e32 v1, 8, v198
	v_bitop3_b32 v3, v3, s12, v2 bitop3:0xde
	v_and_b32_e32 v1, 0x38000, v1
	v_lshlrev_b32_e32 v2, 11, v10
	v_or3_b32 v1, v8, v1, v2
	v_add_u32_e32 v140, v1, v9
	v_lshlrev_b32_e32 v1, 4, v11
	v_and_b32_e32 v1, 0x78000, v1
	s_waitcnt vmcnt(6)
	s_cmpk_lt_u32 s1, 0x100
	v_or3_b32 v1, v8, v1, v2
	s_cselect_b64 s[8:9], -1, 0
	v_add_u32_e32 v142, v1, v9
	s_add_i32 s60, 0, 0x10000
	s_add_i32 s61, 0, 0x14000
	v_mbcnt_lo_u32_b32 v1, -1, 0
	v_lshl_add_u64 v[138:139], s[10:11], 0, v[136:137]
	v_mov_b32_e32 v141, v137
	v_mov_b32_e32 v143, v137
	v_mov_b64_e32 v[144:145], 0x1600
	v_mov_b64_e32 v[146:147], 0x15ff
	v_add_u32_e32 v156, s60, v155
	v_add_u32_e32 v157, s61, v155
	v_add_u32_e32 v158, 0, v3
	v_mbcnt_hi_u32_b32 v159, -1, v1
	v_mov_b32_e32 v160, 0x358637bd
	v_lshlrev_b32_e32 v148, 1, v0
	s_movk_i32 s62, 0x1000
	s_barrier
	s_mov_b32 s10, s63
	s_mov_b32 s12, s18
	s_branch .LBB0_814

;     __host__ __device__ bool next(int i, Unit& u) const {
;         const long L = (long)i * G + c; if (L >= nwg) return false;
;         int wgid = (int)L; { const int q = nwg / NXCD, r = nwg % NXCD, xcd = wgid % NXCD, off = wgid / NXCD; wgid = (xcd < r ? xcd * (q + 1) : r * (q + 1) + (xcd - r) * q) + off; }
;         const int nig = WGM * nN, gid = wgid / nig, fm = gid * WGM, gsz = (nM - fm) < WGM ? (nM - fm) : WGM;
;         u.pm = fm + ((wgid % nig) % gsz); u.pn = (wgid % nig) / gsz; return true;
; template <class Epi, class Sched, bool ALIGN_EPI = false, bool SP2 = false, bool ATILED = false>
; __device__ __forceinline__ void gemm_phase(PG8_LAS unsigned char* lds, const Gemm g, const Sched& S, const Epi& E) {
;     ...
;         const bool has_next = S.next(ui + 1, nxt);
;         const char* nA = has_next ? (const char*)g.A + (size_t)nxt.pm * tstepA : cA; const char* nB = has_next ? (const char*)g.Bt + (size_t)nxt.pn * tstep : cB;
.LBB0_814:
	s_add_i32 s54, s54, 1
	s_add_i32 s10, s10, 4
	s_cmp_ge_u32 s10, 22
	s_cselect_b32 s11, 22, 0
	s_cselect_b32 s13, 8, 0
	s_sub_i32 s10, s10, s11
	s_add_i32 s12, s12, s13
	s_cmp_lt_u32 s54, 22
	s_cselect_b64 s[0:1], -1, 0
